# scan: early-loaded W/U operands read from their landing registers (48 v_mov copies per loop body removed)
# baseline (speedup 1.0000x reference)
; __device__ __forceinline__ f32x4 mfma16(bf16x8 a, bf16x8 b, f32x4 c) { return __builtin_amdgcn_mfma_f32_16x16x32_bf16(a, b, c, 0, 0, 0); }
; __device__ __forceinline__ void scan_step(const ScanCtx& c, int n, const u16* Sc, u16* Sn, f32x4 (&S)[4], bf16x8 (&W_)[2], ...
;     ...
;   bf16x8 Sf[2][4];
; #pragma unroll
;   for (int kb = 0; kb < 2; ++kb)
; #pragma unroll
;     for (int nt = 0; nt < 4; ++nt) Sf[kb][nt] = *(const bf16x8*)(Sc + ((kb * 4 + nt) * 64 + lane) * 8);
; #pragma unroll
;   for (int nt = 0; nt < 4; ++nt) {
;     f32x4 a = {0.f, 0.f, 0.f, 0.f};
;     a = mfma16(W_[0], Sf[0][nt], a); a = mfma16(W_[1], Sf[1][nt], a);
;     f32x4 vn = U_[nt] - a;
.LBB0_483:
	ds_read_b128 v[130:133], v126
	ds_read_b128 v[134:137], v126 offset:1024
	ds_read_b128 v[142:145], v126 offset:2048
	ds_read_b128 v[146:149], v126 offset:3072
	ds_read_b128 v[150:153], v126 offset:4096
	ds_read_b128 v[158:161], v126 offset:5120
	ds_read_b128 v[162:165], v126 offset:6144
	ds_read_b128 v[166:169], v126 offset:7168
	s_waitcnt vmcnt(19)


; __device__ __forceinline__ uint2 pack4v(f32x4 a) { uint2 r; r.x = pack2(a[0], a[1]); r.y = pack2(a[2], a[3]); return r; }
; __device__ __forceinline__ f32x4 mfma16(bf16x8 a, bf16x8 b, f32x4 c) { return __builtin_amdgcn_mfma_f32_16x16x32_bf16(a, b, c, 0, 0, 0); }
; __device__ __forceinline__ void scan_step(const ScanCtx& c, int n, const u16* Sc, u16* Sn, f32x4 (&S)[4], bf16x8 (&W_)[2], ...
;     ...
;   for (int nt = 0; nt < 4; ++nt) {
;     f32x4 a = {0.f, 0.f, 0.f, 0.f};
;     a = mfma16(W_[0], Sf[0][nt], a); a = mfma16(W_[1], Sf[1][nt], a);
;     f32x4 vn = U_[nt] - a;
;     *(uint2*)(c.Vbuf + (((w >> 1) * 4 + nt) * 64 + lane) * 8 + (w & 1) * 4) = pack4v(vn);
;   }
;   __syncthreads();
;   bf16x8 Vf[2][4];
; #pragma unroll
;   for (int kb = 0; kb < 2; ++kb)
; #pragma unroll
;     for (int nt = 0; nt < 4; ++nt) Vf[kb][nt] = *(const bf16x8*)(c.Vbuf + ((kb * 4 + nt) * 64 + lane) * 8);
;   const float glc = g_;
; #pragma unroll
;   for (int nt = 0; nt < 4; ++nt) {
;     f32x4 o = {0.f, 0.f, 0.f, 0.f};
;     o = mfma16(QH_[0], Sf[0][nt], o); o = mfma16(QH_[1], Sf[1][nt], o);
;     o = mfma16(QK_[0], Vf[0][nt], o); o = mfma16(QK_[1], Vf[1][nt], o);
;     *(f32x4*)(c.Obuf + cb + ((w * 4 + nt) * 64 + lane) * 4) = o;
;     f32x4 sv = S[nt] * glc;
;     sv = mfma16(KT_[0], Vf[0][nt], sv); sv = mfma16(KT_[1], Vf[1][nt], sv);
;     S[nt] = sv;
;     *(uint2*)(Sn + (((w >> 1) * 4 + nt) * 64 + lane) * 8 + (w & 1) * 4) = pack4v(sv);
;   }
	v_mov_b32_e32 v118, v194
	v_pk_mul_f32 v[102:103], v[102:103], v[118:119] op_sel_hi:[1,0]
	s_waitcnt lgkmcnt(7)
	v_mfma_f32_16x16x32_bf16 v[138:141], v[170:173], v[130:133], 0
	v_mul_f32_e64 v100, v100, v118
	v_mul_f32_e64 v101, v101, v118
	s_add_i32 s13, s12, 2
	s_waitcnt lgkmcnt(3)
	v_mfma_f32_16x16x32_bf16 v[138:141], v[174:177], v[150:153], v[138:141]
	v_mfma_f32_16x16x32_bf16 v[154:157], v[170:173], v[134:137], 0
	s_nop 6
	v_sub_f32_e32 v79, v181, v141
	v_sub_f32_e32 v78, v180, v140
	v_sub_f32_e32 v77, v179, v139
	v_sub_f32_e32 v76, v178, v138
	v_cvt_pk_bf16_f32 v138, v76, v77
	v_cvt_pk_bf16_f32 v139, v78, v79
	s_waitcnt lgkmcnt(2)
	v_mfma_f32_16x16x32_bf16 v[76:79], v[174:177], v[158:161], v[154:157]
	s_nop 7
	v_sub_f32_e32 v79, v185, v79
	v_sub_f32_e32 v78, v184, v78
	v_sub_f32_e32 v77, v183, v77
	v_sub_f32_e32 v76, v182, v76
	v_mfma_f32_16x16x32_bf16 v[72:75], v[170:173], v[142:145], 0
	v_cvt_pk_bf16_f32 v76, v76, v77
	v_cvt_pk_bf16_f32 v77, v78, v79
	ds_write2st64_b64 v127, v[138:139], v[76:77] offset0:32 offset1:34
	v_mfma_f32_16x16x32_bf16 v[52:55], v[170:173], v[146:149], 0
	v_mul_f32_e64 v78, v110, v118
	v_mul_f32_e64 v79, v111, v118
	v_pk_mul_f32 v[76:77], v[108:109], v[118:119] op_sel_hi:[1,0]
	s_waitcnt lgkmcnt(2)
	v_mfma_f32_16x16x32_bf16 v[72:75], v[174:177], v[162:165], v[72:75]
	s_waitcnt lgkmcnt(1)
	v_mfma_f32_16x16x32_bf16 v[48:51], v[174:177], v[166:169], v[52:55]
	s_nop 5
	v_sub_f32_e32 v71, v189, v75
	v_sub_f32_e32 v70, v188, v74
	v_sub_f32_e32 v69, v187, v73
	v_sub_f32_e32 v68, v186, v72
	v_sub_f32_e32 v51, v193, v51
	v_sub_f32_e32 v50, v192, v50
	v_sub_f32_e32 v49, v191, v49
	v_sub_f32_e32 v48, v190, v48
	v_cvt_pk_bf16_f32 v68, v68, v69
	v_cvt_pk_bf16_f32 v69, v70, v71
	v_cvt_pk_bf16_f32 v48, v48, v49
	v_cvt_pk_bf16_f32 v49, v50, v51
	ds_write_b64 v128, v[68:69] offset:16384
	ds_write_b64 v129, v[48:49] offset:16384
	s_waitcnt vmcnt(13)
	v_mfma_f32_16x16x32_bf16 v[48:51], v[4:7], v[130:133], 0
	s_waitcnt lgkmcnt(0)
	s_barrier
; __device__ __forceinline__ uint2 pack4v(f32x4 a) { uint2 r; r.x = pack2(a[0], a[1]); r.y = pack2(a[2], a[3]); return r; }
; __device__ __forceinline__ f32x4 mfma16(bf16x8 a, bf16x8 b, f32x4 c) { return __builtin_amdgcn_mfma_f32_16x16x32_bf16(a, b, c, 0, 0, 0); }
; __device__ __forceinline__ void scan_load(const ScanCtx& c, int n, bf16x8 (&W_)[2], bf16x8 (&QH_)[2], bf16x8 (&QK_)[2],
;                                           bf16x8 (&KT_)[2], f32x4 (&U_)[4], float& g_) {
;   n = n < 128 ? n : 127;
;   const size_t cb = (size_t)(c.seq * 128 + n) * 4096;
; #pragma unroll
;   for (int kb = 0; kb < 2; ++kb) {
;     const size_t o = cb + ((c.w * 2 + kb) * 64 + c.lane) * 8;
;     W_[kb] = *(const bf16x8*)(c.DNW + o); QH_[kb] = *(const bf16x8*)(c.DNQH + o); QK_[kb] = *(const bf16x8*)(c.DNQK + o); KT_[kb] = *(const bf16x8*)(c.DNKT + o);
;   }
; #pragma unroll
;   for (int nt = 0; nt < 4; ++nt) U_[nt] = *(const f32x4*)(c.Ubuf + cb + ((c.w * 4 + nt) * 64 + c.lane) * 4);
;   g_ = c.glp[c.seq * 128 + n];
; }
; __device__ __forceinline__ void scan_step(const ScanCtx& c, int n, const u16* Sc, u16* Sn, f32x4 (&S)[4], bf16x8 (&W_)[2], ...
;     ...
;   const float glc = g_;
; #pragma unroll
;   for (int nt = 0; nt < 4; ++nt) {
;     f32x4 o = {0.f, 0.f, 0.f, 0.f};
;     o = mfma16(QH_[0], Sf[0][nt], o); o = mfma16(QH_[1], Sf[1][nt], o);
;     o = mfma16(QK_[0], Vf[0][nt], o); o = mfma16(QK_[1], Vf[1][nt], o);
;     *(f32x4*)(c.Obuf + cb + ((w * 4 + nt) * 64 + lane) * 4) = o;
;     f32x4 sv = S[nt] * glc;
;     sv = mfma16(KT_[0], Vf[0][nt], sv); sv = mfma16(KT_[1], Vf[1][nt], sv);
;     S[nt] = sv;
;     *(uint2*)(Sn + (((w >> 1) * 4 + nt) * 64 + lane) * 8 + (w & 1) * 4) = pack4v(sv);
;   }
;   __builtin_amdgcn_sched_barrier(0);
;   scan_load(c, n + 2, W_, QH_, QK_, KT_, U_, g_);
;   {
;     tr[0] ^= tr[1] ^ tr[4];
;     tr[1] = tr[2]; tr[4] = tr[5]; tr[2] = tr[3]; tr[5] = tr[6];
;     const size_t pb = (size_t)(c.seq * 128 + (n + 5 < 128 ? n + 5 : 127)) * 4096;
;     const u16* arr4 = (lane >> 4) == 0 ? c.DNW : ((lane >> 4) == 1 ? c.DNQH : ((lane >> 4) == 2 ? c.DNQK : c.DNKT));
;     tr[3] = *(const unsigned*)(arr4 + pb + w * 1024 + (lane & 15) * 64);
;     tr[6] = *(const unsigned*)(c.Ubuf + pb + w * 1024 + (lane & 31) * 32);
;   }
;   __syncthreads();
; }
	s_min_u32 s24, s13, 0x7d
	s_add_i32 s24, s24, s8
	s_ashr_i32 s25, s24, 31
	s_lshl_b64 s[26:27], s[24:25], 12
	v_lshl_add_u64 v[222:223], s[26:27], 0, v[112:113]
	v_lshlrev_b64 v[222:223], 1, v[222:223]
	v_lshl_add_u64 v[222:223], s[20:21], 0, v[222:223]
	s_lshl_b64 s[26:27], s[24:25], 14
	v_lshl_add_u64 v[224:225], v[116:117], 0, s[26:27]
	s_lshl_b64 s[28:29], s[24:25], 2
	s_add_u32 s28, s10, s28
	s_addc_u32 s29, s11, s29
	global_load_dwordx4 v[170:173], v[222:223], off
	global_load_dwordx4 v[174:177], v[222:223], off offset:1024
	global_load_dwordx4 v[178:181], v[224:225], off
	global_load_dwordx4 v[182:185], v[224:225], off offset:1024
	global_load_dwordx4 v[186:189], v[224:225], off offset:2048
	global_load_dwordx4 v[190:193], v[224:225], off offset:3072
	global_load_dword v194, v125, s[28:29]
	v_mfma_f32_16x16x32_bf16 v[48:51], v[16:19], v[150:153], v[48:51]
	ds_read_b128 v[52:55], v126 offset:16384
	ds_read_b128 v[64:67], v126 offset:17408
	ds_read_b128 v[68:71], v126 offset:20480
	ds_read_b128 v[72:75], v126 offset:21504
	s_waitcnt lgkmcnt(3)
	v_mfma_f32_16x16x32_bf16 v[48:51], v[0:3], v[52:55], v[48:51]
	v_mfma_f32_16x16x32_bf16 v[52:55], v[8:11], v[52:55], v[76:79]
	s_waitcnt lgkmcnt(1)
	v_mfma_f32_16x16x32_bf16 v[108:111], v[12:15], v[68:71], v[52:55]
	v_mfma_f32_16x16x32_bf16 v[52:55], v[4:7], v[134:137], 0
	v_mfma_f32_16x16x32_bf16 v[52:55], v[16:19], v[158:161], v[52:55]
	v_mfma_f32_16x16x32_bf16 v[48:51], v[20:23], v[68:71], v[48:51]
	v_mul_f32_e64 v70, v106, v118
	v_mul_f32_e64 v71, v107, v118
	v_pk_mul_f32 v[68:69], v[104:105], v[118:119] op_sel_hi:[1,0]
	v_mfma_f32_16x16x32_bf16 v[52:55], v[0:3], v[64:67], v[52:55]
	s_nop 0
	v_mfma_f32_16x16x32_bf16 v[64:67], v[8:11], v[64:67], v[68:71]
	s_waitcnt lgkmcnt(0)
	v_mfma_f32_16x16x32_bf16 v[104:107], v[12:15], v[72:75], v[64:67]
	v_mfma_f32_16x16x32_bf16 v[64:67], v[4:7], v[142:145], 0
	v_mfma_f32_16x16x32_bf16 v[4:7], v[4:7], v[146:149], 0
	v_mfma_f32_16x16x32_bf16 v[52:55], v[20:23], v[72:75], v[52:55]
	ds_read_b128 v[68:71], v126 offset:18432
	ds_read_b128 v[72:75], v126 offset:19456
	ds_read_b128 v[76:79], v126 offset:22528
	ds_read_b128 v[130:133], v126 offset:23552
	v_mfma_f32_16x16x32_bf16 v[64:67], v[16:19], v[162:165], v[64:67]
	v_mfma_f32_16x16x32_bf16 v[4:7], v[16:19], v[166:169], v[4:7]
	v_cvt_pk_bf16_f32 v16, v104, v105
	v_cvt_pk_bf16_f32 v17, v106, v107
	s_waitcnt lgkmcnt(3)
	v_mfma_f32_16x16x32_bf16 v[64:67], v[0:3], v[68:71], v[64:67]
	s_waitcnt lgkmcnt(2)
	v_mfma_f32_16x16x32_bf16 v[0:3], v[0:3], v[72:75], v[4:7]
	s_nop 2
	v_mul_f32_e64 v6, v98, v118
	v_mul_f32_e64 v7, v99, v118
	v_pk_mul_f32 v[4:5], v[96:97], v[118:119] op_sel_hi:[1,0]
	v_mfma_f32_16x16x32_bf16 v[68:71], v[8:11], v[68:71], v[100:103]
	s_nop 0
	v_mfma_f32_16x16x32_bf16 v[4:7], v[8:11], v[72:75], v[4:7]
	s_waitcnt lgkmcnt(1)
	v_mfma_f32_16x16x32_bf16 v[100:103], v[12:15], v[76:79], v[68:71]
	s_waitcnt lgkmcnt(0)
	v_mfma_f32_16x16x32_bf16 v[0:3], v[20:23], v[130:133], v[0:3]
	s_nop 1
	v_add_co_u32_e32 v68, vcc, s9, v120
	v_mfma_f32_16x16x32_bf16 v[96:99], v[12:15], v[130:133], v[4:7]
	s_nop 0
	v_addc_co_u32_e32 v69, vcc, -1, v121, vcc
	global_store_dwordx4 v[68:69], v[48:51], off offset:-3072
	v_mfma_f32_16x16x32_bf16 v[64:67], v[20:23], v[76:79], v[64:67]
	global_store_dwordx4 v[68:69], v[0:3], off
	v_cvt_pk_bf16_f32 v48, v108, v109
	v_cvt_pk_bf16_f32 v49, v110, v111
	ds_write2st64_b64 v127, v[48:49], v[16:17] offset0:16 offset1:18
	v_cvt_pk_bf16_f32 v16, v100, v101
	v_cvt_pk_bf16_f32 v17, v102, v103
	v_cvt_pk_bf16_f32 v0, v96, v97
	v_cvt_pk_bf16_f32 v1, v98, v99
	global_store_dwordx4 v[68:69], v[52:55], off offset:-2048
	global_store_dwordx4 v[68:69], v[64:67], off offset:-1024
	ds_write_b64 v128, v[16:17] offset:8192
	ds_write_b64 v129, v[0:1] offset:8192
	s_min_u32 s14, s13, 0x7d
	s_add_i32 s14, s14, s8
	s_ashr_i32 s15, s14, 31
	s_lshl_b64 s[16:17], s[14:15], 12
	v_lshl_add_u64 v[0:1], s[16:17], 0, v[112:113]
	v_lshlrev_b64 v[8:9], 1, v[0:1]
	v_lshl_add_u64 v[12:13], s[0:1], 0, v[8:9]
	v_lshl_add_u64 v[10:11], s[20:21], 0, v[8:9]
	v_lshl_add_u64 v[14:15], s[2:3], 0, v[8:9]
	global_load_dwordx4 v[4:7], v[12:13], off
	global_load_dwordx4 v[0:3], v[14:15], off
	v_lshl_add_u64 v[12:13], s[4:5], 0, v[8:9]
	v_lshl_add_u64 v[8:9], s[16:17], 0, v[114:115]
	v_lshlrev_b64 v[14:15], 1, v[8:9]
	v_lshl_add_u64 v[20:21], s[0:1], 0, v[14:15]
	v_lshl_add_u64 v[64:65], s[2:3], 0, v[14:15]
	s_lshl_b64 s[16:17], s[14:15], 14
	s_nop 0
	s_nop 0
	s_nop 0
	global_load_dwordx4 v[8:11], v[12:13], off
	global_load_dwordx4 v[16:19], v[20:21], off
	v_lshl_add_u64 v[66:67], s[4:5], 0, v[14:15]
	global_load_dwordx4 v[20:23], v[64:65], off
	global_load_dwordx4 v[12:15], v[66:67], off
	v_lshl_add_u64 v[64:65], v[116:117], 0, s[16:17]
	s_lshl_b64 s[14:15], s[14:15], 2
	s_nop 0
	s_nop 0
	s_nop 0
	s_nop 0
	s_nop 0
	s_add_u32 s14, s10, s14
	s_addc_u32 s15, s11, s15
	s_nop 0
	s_waitcnt lgkmcnt(0)
	s_barrier
	ds_read_b128 v[130:133], v126 offset:8192
	ds_read_b128 v[134:137], v126 offset:9216
	ds_read_b128 v[138:141], v126 offset:10240
	ds_read_b128 v[142:145], v126 offset:11264
	ds_read_b128 v[146:149], v126 offset:12288
	s_waitcnt vmcnt(19) lgkmcnt(4)


; __device__ __forceinline__ uint2 pack4v(f32x4 a) { uint2 r; r.x = pack2(a[0], a[1]); r.y = pack2(a[2], a[3]); return r; }
; __device__ __forceinline__ f32x4 mfma16(bf16x8 a, bf16x8 b, f32x4 c) { return __builtin_amdgcn_mfma_f32_16x16x32_bf16(a, b, c, 0, 0, 0); }
; __device__ __forceinline__ void scan_step(const ScanCtx& c, int n, const u16* Sc, u16* Sn, f32x4 (&S)[4], bf16x8 (&W_)[2], ...
;     ...
;   bf16x8 Sf[2][4];
; #pragma unroll
;   for (int kb = 0; kb < 2; ++kb)
; #pragma unroll
;     for (int nt = 0; nt < 4; ++nt) Sf[kb][nt] = *(const bf16x8*)(Sc + ((kb * 4 + nt) * 64 + lane) * 8);
; #pragma unroll
;   for (int nt = 0; nt < 4; ++nt) {
;     f32x4 a = {0.f, 0.f, 0.f, 0.f};
;     a = mfma16(W_[0], Sf[0][nt], a); a = mfma16(W_[1], Sf[1][nt], a);
;     f32x4 vn = U_[nt] - a;
;     *(uint2*)(c.Vbuf + (((w >> 1) * 4 + nt) * 64 + lane) * 8 + (w & 1) * 4) = pack4v(vn);
;   }
;   __syncthreads();
;   bf16x8 Vf[2][4];
; #pragma unroll
;   for (int kb = 0; kb < 2; ++kb)
; #pragma unroll
;     for (int nt = 0; nt < 4; ++nt) Vf[kb][nt] = *(const bf16x8*)(c.Vbuf + ((kb * 4 + nt) * 64 + lane) * 8);
;   const float glc = g_;
; #pragma unroll
;   for (int nt = 0; nt < 4; ++nt) {
;     f32x4 o = {0.f, 0.f, 0.f, 0.f};
;     o = mfma16(QH_[0], Sf[0][nt], o); o = mfma16(QH_[1], Sf[1][nt], o);
;     o = mfma16(QK_[0], Vf[0][nt], o); o = mfma16(QK_[1], Vf[1][nt], o);
;     *(f32x4*)(c.Obuf + cb + ((w * 4 + nt) * 64 + lane) * 4) = o;
;     f32x4 sv = S[nt] * glc;
;     sv = mfma16(KT_[0], Vf[0][nt], sv); sv = mfma16(KT_[1], Vf[1][nt], sv);
;     S[nt] = sv;
;     *(uint2*)(Sn + (((w >> 1) * 4 + nt) * 64 + lane) * 8 + (w & 1) * 4) = pack4v(sv);
;   }
	v_mov_b32_e32 v122, v195
	v_mfma_f32_16x16x32_bf16 v[150:153], v[196:199], v[130:133], 0
	ds_read_b128 v[154:157], v126 offset:13312
	ds_read_b128 v[158:161], v126 offset:14336
	ds_read_b128 v[162:165], v126 offset:15360
	s_nop 0
	v_pk_mul_f32 v[102:103], v[122:123], v[102:103] op_sel_hi:[0,1]
	v_pk_mul_f32 v[100:101], v[122:123], v[100:101] op_sel_hi:[0,1]
	s_waitcnt lgkmcnt(3)
	v_mfma_f32_16x16x32_bf16 v[150:153], v[200:203], v[146:149], v[150:153]
	s_add_i32 s12, s12, 3
	v_mfma_f32_16x16x32_bf16 v[166:169], v[196:199], v[134:137], 0
	s_nop 0
	s_nop 4
	v_sub_f32_e32 v95, v207, v153
	v_sub_f32_e32 v94, v206, v152
	v_sub_f32_e32 v93, v205, v151
	v_sub_f32_e32 v92, v204, v150
	v_cvt_pk_bf16_f32 v150, v92, v93
	v_cvt_pk_bf16_f32 v151, v94, v95
	s_waitcnt lgkmcnt(2)
	v_mfma_f32_16x16x32_bf16 v[92:95], v[200:203], v[154:157], v[166:169]
	s_nop 0
	s_nop 6
	v_sub_f32_e32 v95, v211, v95
	v_sub_f32_e32 v94, v210, v94
	v_sub_f32_e32 v93, v209, v93
	v_sub_f32_e32 v92, v208, v92
	v_mfma_f32_16x16x32_bf16 v[88:91], v[196:199], v[138:141], 0
	v_cvt_pk_bf16_f32 v92, v92, v93
	v_cvt_pk_bf16_f32 v93, v94, v95
	ds_write2st64_b64 v127, v[150:151], v[92:93] offset0:32 offset1:34
	v_mfma_f32_16x16x32_bf16 v[60:63], v[196:199], v[142:145], 0
	v_mul_f32_e64 v94, v122, v110
	v_mul_f32_e64 v95, v122, v111
	v_pk_mul_f32 v[92:93], v[122:123], v[108:109] op_sel_hi:[0,1]
	s_waitcnt lgkmcnt(2)
	v_mfma_f32_16x16x32_bf16 v[88:91], v[200:203], v[158:161], v[88:91]
	s_waitcnt lgkmcnt(1)
	v_mfma_f32_16x16x32_bf16 v[56:59], v[200:203], v[162:165], v[60:63]
	s_nop 0
	s_nop 4
	v_sub_f32_e32 v87, v215, v91
	v_sub_f32_e32 v86, v214, v90
	v_sub_f32_e32 v85, v213, v89
	v_sub_f32_e32 v84, v212, v88
	s_nop 0
	v_sub_f32_e32 v59, v219, v59
	v_sub_f32_e32 v58, v218, v58
	v_sub_f32_e32 v57, v217, v57
	v_sub_f32_e32 v56, v216, v56
	v_cvt_pk_bf16_f32 v84, v84, v85
	v_cvt_pk_bf16_f32 v85, v86, v87
	v_cvt_pk_bf16_f32 v56, v56, v57
	v_cvt_pk_bf16_f32 v57, v58, v59
	ds_write_b64 v128, v[84:85] offset:16384
	ds_write_b64 v129, v[56:57] offset:16384
	s_waitcnt vmcnt(13)
	v_mfma_f32_16x16x32_bf16 v[56:59], v[28:31], v[130:133], 0
	s_waitcnt lgkmcnt(0)
	s_barrier
; __device__ __forceinline__ void scan_load(const ScanCtx& c, int n, bf16x8 (&W_)[2], bf16x8 (&QH_)[2], bf16x8 (&QK_)[2],
;                                           bf16x8 (&KT_)[2], f32x4 (&U_)[4], float& g_) {
;   n = n < 128 ? n : 127;
;   const size_t cb = (size_t)(c.seq * 128 + n) * 4096;
; #pragma unroll
;   for (int kb = 0; kb < 2; ++kb) {
;     const size_t o = cb + ((c.w * 2 + kb) * 64 + c.lane) * 8;
;     W_[kb] = *(const bf16x8*)(c.DNW + o); QH_[kb] = *(const bf16x8*)(c.DNQH + o); QK_[kb] = *(const bf16x8*)(c.DNQK + o); KT_[kb] = *(const bf16x8*)(c.DNKT + o);
;   }
; #pragma unroll
;   for (int nt = 0; nt < 4; ++nt) U_[nt] = *(const f32x4*)(c.Ubuf + cb + ((c.w * 4 + nt) * 64 + c.lane) * 4);
;   g_ = c.glp[c.seq * 128 + n];
; }
; __device__ void scan_seq(const P& p, int seq, u16* lds) {
;     ...
; #pragma unroll 1
;   for (int n = 0; n < 128; n += 2) {
;     scan_step(c, n, Sb0, Sb1, S, Wa, QHa, QKa, KTa, Ua, ga, tr);
;     scan_step(c, n + 1, Sb1, Sb0, S, Wb, QHb, QKb, KTb, Ub, gb, tr);
;   }
;   if ((tr[0] ^ tr[1] ^ tr[2] ^ tr[3] ^ tr[4] ^ tr[5] ^ tr[6]) == 0x9e3779b9u && seq == 4097) p_gl[0] = 0.f;
; #pragma unroll
;   for (int nt = 0; nt < 4; ++nt)
; #pragma unroll
;     for (int r = 0; r < 4; ++r) p.out[O_DP + ((size_t)seq * 64 + w * 16 + fq * 4 + r) * 64 + nt * 16 + fr] = S[nt][r];
	s_min_u32 s24, s12, 0x7d
	s_add_i32 s24, s24, s8
	s_ashr_i32 s25, s24, 31
	s_lshl_b64 s[26:27], s[24:25], 12
	v_lshl_add_u64 v[222:223], s[26:27], 0, v[112:113]
	v_lshlrev_b64 v[222:223], 1, v[222:223]
	v_lshl_add_u64 v[222:223], s[20:21], 0, v[222:223]
	s_lshl_b64 s[26:27], s[24:25], 14
	v_lshl_add_u64 v[224:225], v[116:117], 0, s[26:27]
	s_lshl_b64 s[28:29], s[24:25], 2
	s_add_u32 s28, s10, s28
	s_addc_u32 s29, s11, s29
	global_load_dwordx4 v[196:199], v[222:223], off
	global_load_dwordx4 v[200:203], v[222:223], off offset:1024
	global_load_dwordx4 v[204:207], v[224:225], off
	global_load_dwordx4 v[208:211], v[224:225], off offset:1024
	global_load_dwordx4 v[212:215], v[224:225], off offset:2048
	global_load_dwordx4 v[216:219], v[224:225], off offset:3072
	global_load_dword v195, v125, s[28:29]
	v_mfma_f32_16x16x32_bf16 v[56:59], v[40:43], v[146:149], v[56:59]
	ds_read_b128 v[60:63], v126 offset:16384
	ds_read_b128 v[80:83], v126 offset:17408
	ds_read_b128 v[84:87], v126 offset:20480
	ds_read_b128 v[88:91], v126 offset:21504
	s_waitcnt lgkmcnt(3)
	v_mfma_f32_16x16x32_bf16 v[56:59], v[24:27], v[60:63], v[56:59]
	v_mfma_f32_16x16x32_bf16 v[60:63], v[32:35], v[60:63], v[92:95]
	s_waitcnt lgkmcnt(1)
	v_mfma_f32_16x16x32_bf16 v[108:111], v[36:39], v[84:87], v[60:63]
	v_mfma_f32_16x16x32_bf16 v[60:63], v[28:31], v[134:137], 0
	v_mfma_f32_16x16x32_bf16 v[60:63], v[40:43], v[154:157], v[60:63]
	v_mfma_f32_16x16x32_bf16 v[56:59], v[44:47], v[84:87], v[56:59]
	v_mul_f32_e64 v86, v122, v106
	v_mul_f32_e64 v87, v122, v107
	v_pk_mul_f32 v[84:85], v[122:123], v[104:105] op_sel_hi:[0,1]
	v_mfma_f32_16x16x32_bf16 v[60:63], v[24:27], v[80:83], v[60:63]
	s_nop 0
	v_mfma_f32_16x16x32_bf16 v[80:83], v[32:35], v[80:83], v[84:87]
	s_waitcnt lgkmcnt(0)
	v_mfma_f32_16x16x32_bf16 v[104:107], v[36:39], v[88:91], v[80:83]
	v_mfma_f32_16x16x32_bf16 v[80:83], v[28:31], v[138:141], 0
	v_mfma_f32_16x16x32_bf16 v[28:31], v[28:31], v[142:145], 0
	v_mfma_f32_16x16x32_bf16 v[60:63], v[44:47], v[88:91], v[60:63]
	ds_read_b128 v[84:87], v126 offset:18432
	ds_read_b128 v[88:91], v126 offset:19456
	ds_read_b128 v[92:95], v126 offset:22528
	ds_read_b128 v[130:133], v126 offset:23552
	global_store_dwordx4 v[120:121], v[56:59], off offset:-3072
	v_mfma_f32_16x16x32_bf16 v[80:83], v[40:43], v[158:161], v[80:83]
	s_nop 1
	global_store_dwordx4 v[120:121], v[60:63], off offset:-2048
	v_cvt_pk_bf16_f32 v56, v108, v109
	v_cvt_pk_bf16_f32 v57, v110, v111
	v_mfma_f32_16x16x32_bf16 v[28:31], v[40:43], v[162:165], v[28:31]
	v_cvt_pk_bf16_f32 v40, v104, v105
	v_cvt_pk_bf16_f32 v41, v106, v107
	ds_write2st64_b64 v127, v[56:57], v[40:41] offset1:2
	s_waitcnt lgkmcnt(4)
	v_mfma_f32_16x16x32_bf16 v[80:83], v[24:27], v[84:87], v[80:83]
	s_waitcnt lgkmcnt(3)
	v_mfma_f32_16x16x32_bf16 v[24:27], v[24:27], v[88:91], v[28:31]
	s_nop 2
	v_mul_f32_e64 v30, v122, v98
	v_mul_f32_e64 v31, v122, v99
	v_pk_mul_f32 v[28:29], v[122:123], v[96:97] op_sel_hi:[0,1]
	v_mfma_f32_16x16x32_bf16 v[84:87], v[32:35], v[84:87], v[100:103]
	s_nop 0
	v_mfma_f32_16x16x32_bf16 v[28:31], v[32:35], v[88:91], v[28:31]
	s_waitcnt lgkmcnt(2)
	v_mfma_f32_16x16x32_bf16 v[100:103], v[36:39], v[92:95], v[84:87]
	s_waitcnt lgkmcnt(1)
	v_mfma_f32_16x16x32_bf16 v[24:27], v[44:47], v[130:133], v[24:27]
	v_mfma_f32_16x16x32_bf16 v[96:99], v[36:39], v[130:133], v[28:31]
	s_nop 4
	v_cvt_pk_bf16_f32 v40, v100, v101
	v_cvt_pk_bf16_f32 v41, v102, v103
	global_store_dwordx4 v[120:121], v[24:27], off
	v_mfma_f32_16x16x32_bf16 v[80:83], v[44:47], v[92:95], v[80:83]
	ds_write_b64 v128, v[40:41]
	v_cvt_pk_bf16_f32 v24, v96, v97
	v_cvt_pk_bf16_f32 v25, v98, v99
	ds_write_b64 v129, v[24:25]
	s_nop 3
	global_store_dwordx4 v[120:121], v[80:83], off offset:-1024
	s_min_u32 s12, s12, 0x7d
	s_add_i32 s14, s12, s8
	s_ashr_i32 s15, s14, 31
	s_lshl_b64 s[16:17], s[14:15], 12
	v_lshl_add_u64 v[24:25], s[16:17], 0, v[112:113]
	v_lshlrev_b64 v[32:33], 1, v[24:25]
	v_lshl_add_u64 v[34:35], s[20:21], 0, v[32:33]
	v_lshl_add_u64 v[24:25], s[0:1], 0, v[32:33]
	v_lshl_add_u64 v[26:27], s[2:3], 0, v[32:33]
	v_lshl_add_u64 v[36:37], s[4:5], 0, v[32:33]
	v_lshl_add_u64 v[32:33], s[16:17], 0, v[114:115]
	v_lshlrev_b64 v[38:39], 1, v[32:33]
	v_lshl_add_u64 v[44:45], s[0:1], 0, v[38:39]
	v_lshl_add_u64 v[80:81], s[2:3], 0, v[38:39]
	s_lshl_b64 s[16:17], s[14:15], 14
	global_load_dwordx4 v[28:31], v[24:25], off
	s_nop 0
	global_load_dwordx4 v[24:27], v[26:27], off
	s_nop 0
	s_nop 0
	s_nop 0
	s_nop 0
	global_load_dwordx4 v[32:35], v[36:37], off
	global_load_dwordx4 v[40:43], v[44:45], off
	v_lshl_add_u64 v[82:83], s[4:5], 0, v[38:39]
	global_load_dwordx4 v[44:47], v[80:81], off
	global_load_dwordx4 v[36:39], v[82:83], off
	v_lshl_add_u64 v[80:81], v[116:117], 0, s[16:17]
	s_lshl_b64 s[14:15], s[14:15], 2
	s_nop 0
	s_nop 0
	s_nop 0
	s_nop 0
	s_nop 0
	s_add_u32 s14, s10, s14
	s_addc_u32 s15, s11, s15
	s_nop 0
	v_lshl_add_u64 v[120:121], v[120:121], 0, s[6:7]
	s_cmpk_lt_u32 s13, 0x7e
	s_mov_b32 s12, s13
	s_waitcnt lgkmcnt(0)
	s_barrier
	s_cbranch_scc1 .LBB0_483
	v_readlane_b32 s0, v228, 0
	v_readlane_b32 s1, v228, 1
	s_mov_b32 s2, s0
	s_ashr_i32 s3, s0, 31
	v_writelane_b32 v228, s0, 0
	s_waitcnt vmcnt(0)
	v_lshlrev_b32_e32 v0, 4, v124
	v_ashrrev_i32_e32 v1, 31, v0
	v_writelane_b32 v228, s1, 1
	s_lshl_b64 s[0:1], s[2:3], 6
	v_lshl_add_u64 v[0:1], s[0:1], 0, v[0:1]
	v_lshrrev_b32_e32 v3, 2, v123
	v_and_or_b32 v0, v3, 12, v0
	v_and_b32_e32 v2, 15, v123
	v_lshlrev_b64 v[0:1], 8, v[0:1]
	v_lshl_add_u64 v[0:1], s[20:21], 0, v[0:1]
	v_lshlrev_b32_e32 v2, 2, v2
	v_mov_b32_e32 v3, 0
	v_lshl_add_u64 v[0:1], v[0:1], 0, v[2:3]
	s_mov_b32 s0, 0x8492000
	v_add_co_u32_e32 v0, vcc, s0, v0
	s_nop 1
	v_addc_co_u32_e32 v1, vcc, 0, v1, vcc
	global_store_dword v[0:1], v108, off
	global_store_dword v[0:1], v109, off offset:256
	global_store_dword v[0:1], v110, off offset:512
	global_store_dword v[0:1], v111, off offset:768
	global_store_dword v[0:1], v104, off offset:64
	global_store_dword v[0:1], v105, off offset:320
	global_store_dword v[0:1], v106, off offset:576
	global_store_dword v[0:1], v107, off offset:832
	global_store_dword v[0:1], v100, off offset:128
	global_store_dword v[0:1], v101, off offset:384
	global_store_dword v[0:1], v102, off offset:640
	global_store_dword v[0:1], v103, off offset:896
	global_store_dword v[0:1], v96, off offset:192
	global_store_dword v[0:1], v97, off offset:448
	global_store_dword v[0:1], v98, off offset:704
	global_store_dword v[0:1], v99, off offset:960
